# no static priority raise in the fast-path attention units (equal wave priority); on top of v18
# speedup vs baseline: 1.0073x; 1.0073x over previous
; template<int THRL,int VM,bool NOMAX> __device__ __forceinline__ void attn_unit(const bf16*Qb,const bf16*__restrict__ Kh,const bf16*__restrict__ Vh,bf16*Ob,const int NT,const int sp,float*wscr,char*shm){
;   int tid_=threadIdx.x; asm volatile("":"+v"(tid_));
;   const int tid=tid_,lane=tid&63,r32=lane&31,hi=lane>>5; const int wid=__builtin_amdgcn_readfirstlane(tid>>6);
;   const bf16*Qw=Qb+(long)(wid*QBLK)*QOP;
;   const unsigned lds0=(unsigned)(uintptr_t)shm;
;   constexpr int LDS_WS_=LDS_V+3*VM*SLOTB, LDS_OST_=LDS_WS_+NW*64*4;
;   float*wsf=(float*)(shm+LDS_WS_)+wid*64;
;   const bf16*ksrc=Kh+(long)lane*KVP+wid*8;
;   const bf16*vsrc=Vh+(long)(16*(wid&3)+(lane>>2))*KVP+(wid>>2)*32+(lane&3)*8;
;   const unsigned kdst=lds0+LDS_K+wid*1024, vdst=lds0+LDS_V+wid*1024;
;     ...
;   const int vb0=(int)(lds0+LDS_V)+((lane>>4)&1)*32+(lane&3)*8+(4*hi+((lane&15)>>2))*64;
;   const char*Kbase=shm+LDS_K; bf16x8 kf[8];
;   const lds_cptr shm3=(lds_cptr)shm; const lds_cptr kp0=shm3+LDS_K+hi*1024+r32*16; const lds_cptr vp0=shm3+LDS_V+((lane>>4)&1)*32+(lane&3)*8+(4*hi+((lane&15)>>2))*64;
;   if(wid>=4)__builtin_amdgcn_s_setprio(1);
.LBB0_860:
	v_mov_b32_e32 v32, v210
	s_nop 0
	v_readfirstlane_b32 s34, v32
	s_ashr_i32 s85, s34, 6
	s_cmp_lt_i32 s85, 4
	s_cbranch_scc1 .LBB0_862
	s_setprio 0

; template<int THRL,int VM,bool NOMAX> __device__ __forceinline__ void attn_unit(const bf16*Qb,const bf16*__restrict__ Kh,const bf16*__restrict__ Vh,bf16*Ob,const int NT,const int sp,float*wscr,char*shm){
;   int tid_=threadIdx.x; asm volatile("":"+v"(tid_));
;   const int tid=tid_,lane=tid&63,r32=lane&31,hi=lane>>5; const int wid=__builtin_amdgcn_readfirstlane(tid>>6);
;   const bf16*Qw=Qb+(long)(wid*QBLK)*QOP;
;   const unsigned lds0=(unsigned)(uintptr_t)shm;
;   constexpr int LDS_WS_=LDS_V+3*VM*SLOTB, LDS_OST_=LDS_WS_+NW*64*4;
;   float*wsf=(float*)(shm+LDS_WS_)+wid*64;
;   const bf16*ksrc=Kh+(long)lane*KVP+wid*8;
;   const bf16*vsrc=Vh+(long)(16*(wid&3)+(lane>>2))*KVP+(wid>>2)*32+(lane&3)*8;
;   const unsigned kdst=lds0+LDS_K+wid*1024, vdst=lds0+LDS_V+wid*1024;
;     ...
;   const int vb0=(int)(lds0+LDS_V)+((lane>>4)&1)*32+(lane&3)*8+(4*hi+((lane&15)>>2))*64;
;   const char*Kbase=shm+LDS_K; bf16x8 kf[8];
;   const lds_cptr shm3=(lds_cptr)shm; const lds_cptr kp0=shm3+LDS_K+hi*1024+r32*16; const lds_cptr vp0=shm3+LDS_V+((lane>>4)&1)*32+(lane&3)*8+(4*hi+((lane&15)>>2))*64;
;   if(wid>=4)__builtin_amdgcn_s_setprio(1);
.LBB0_879:
	v_mov_b32_e32 v48, v210
	s_nop 0
	v_readfirstlane_b32 s29, v48
	s_ashr_i32 s28, s29, 6
	s_cmp_lt_i32 s28, 4
	s_cbranch_scc1 .LBB0_881
	s_setprio 0

; template<int THRL,int VM,bool NOMAX> __device__ __forceinline__ void attn_unit(const bf16*Qb,const bf16*__restrict__ Kh,const bf16*__restrict__ Vh,bf16*Ob,const int NT,const int sp,float*wscr,char*shm){
;   int tid_=threadIdx.x; asm volatile("":"+v"(tid_));
;   const int tid=tid_,lane=tid&63,r32=lane&31,hi=lane>>5; const int wid=__builtin_amdgcn_readfirstlane(tid>>6);
;   const bf16*Qw=Qb+(long)(wid*QBLK)*QOP;
;   const unsigned lds0=(unsigned)(uintptr_t)shm;
;   constexpr int LDS_WS_=LDS_V+3*VM*SLOTB, LDS_OST_=LDS_WS_+NW*64*4;
;   float*wsf=(float*)(shm+LDS_WS_)+wid*64;
;   const bf16*ksrc=Kh+(long)lane*KVP+wid*8;
;   const bf16*vsrc=Vh+(long)(16*(wid&3)+(lane>>2))*KVP+(wid>>2)*32+(lane&3)*8;
;   const unsigned kdst=lds0+LDS_K+wid*1024, vdst=lds0+LDS_V+wid*1024;
;     ...
;   const int vb0=(int)(lds0+LDS_V)+((lane>>4)&1)*32+(lane&3)*8+(4*hi+((lane&15)>>2))*64;
;   const char*Kbase=shm+LDS_K; bf16x8 kf[8];
;   const lds_cptr shm3=(lds_cptr)shm; const lds_cptr kp0=shm3+LDS_K+hi*1024+r32*16; const lds_cptr vp0=shm3+LDS_V+((lane>>4)&1)*32+(lane&3)*8+(4*hi+((lane&15)>>2))*64;
;   if(wid>=4)__builtin_amdgcn_s_setprio(1);
.LBB0_888:
	v_mov_b32_e32 v48, v210
	s_nop 0
	v_readfirstlane_b32 s19, v48
	s_ashr_i32 s18, s19, 6
	s_cmp_lt_i32 s18, 4
	s_cbranch_scc1 .LBB0_890
	s_setprio 0
